# diff-attn v128 max-free unit: K tile staged as whole 128-byte rows (row-group pieces, XOR-swizzled chunks) so each K LDS-DMA touches 8 cache lines instead of 64; on top of v1
# speedup vs baseline: 1.0103x; 1.0015x over previous
; __device__ __forceinline__ float fsub_s(float a,float b){float r;asm("v_sub_f32_e32 %0, %1, %2":"=v"(r):"v"(a),"v"(b));return r;}
; #define WAIT_BAR(N) asm volatile("s_waitcnt vmcnt(" #N ") lgkmcnt(0)\n\ts_barrier":::"memory")
;   #define DMA_K(t,slot) glds16(ksrc+(long)(t)*KVBLK*kp,(unsigned)__builtin_amdgcn_readfirstlane(kdst+(slot)))
;   #define DMA_V(t,slot) glds16(vsrc+(long)(t)*KVBLK*vp,(unsigned)__builtin_amdgcn_readfirstlane(vdst+(slot)))
; template<int THRL,bool NOMAX=false> __device__ __forceinline__ void attn_unit_v128(const bf16*Qu,int qp,const bf16*__restrict__ Kh,int kp,const bf16*__restrict__ Vh,int vp,bf16*Ou,int op,int NT,char*shm,int tid_in){
;   int tid_=tid_in; asm volatile("":"+v"(tid_));
;   const int tid=tid_,lane=tid&63,r32=lane&31,hi=lane>>5; const int wid=__builtin_amdgcn_readfirstlane(tid>>6);
;   const bf16*Qw=Qu+(long)(wid*QBLK)*qp;
;   const unsigned lds0=(unsigned)(uintptr_t)shm;
;   float*wsf=(float*)(shm+V2_LDS_WS)+wid*64;
;   const bf16*ksrc=Kh+(long)lane*kp+wid*8;
;   const bf16*vsrc=Vh+(long)(16*(wid&3)+(lane>>2))*vp+(wid>>2)*32+(lane&3)*8;
;   const unsigned kdst=lds0+V2_LDS_K+wid*1024, vdst=lds0+V2_LDS_V+wid*1024;
;     ...
;   const int vb0=(int)(lds0+V2_LDS_V)+((lane>>4)&1)*32+(lane&3)*8+(4*hi+((lane&15)>>2))*64;
;   const char*Kbase=shm+V2_LDS_K; bf16x8 kf[8];
;   const lds_cptr shm3=(lds_cptr)shm; const lds_cptr kp0=shm3+V2_LDS_K+hi*1024+r32*16; const lds_cptr vp0=shm3+V2_LDS_V+((lane>>4)&1)*32+(lane&3)*8+(4*hi+((lane&15)>>2))*64;
;   DMA_K(0,0);DMA_V(0,0);DMA_K(1,SLOTB);
;   bf16x8 qr[4];
;   #pragma unroll
;   for(int d0=0;d0<4;++d0)qr[d0]=*reinterpret_cast<const bf16x8*>(&Qw[(long)r32*qp+d0*16+hi*8]);
;   float mhat=0.f,l_reg=0.f;f32x16 o[4];o[0]=f32x16{};o[1]=f32x16{};o[2]=f32x16{};o[3]=f32x16{};
;   const f32x16 zero16=f32x16{};
;   bool resc=false;
;     ...
;   f32x16 pA0,pA1,pB0,pB1;
;   int sl_prev=0,sl_cur=0,sl_next=SLOTB;
;     ...
;   DMA_K(2,2*SLOTB);
;   WAIT_BAR(3);
;   qkt0(pA0,pA1,Kbase,qr,r32,hi);asm volatile("s_nop 15\n\ts_nop 7":"+v"(pA0),"+v"(pA1));
;   START(pA0,pA1);
;   if constexpr(NOMAX){ _Pragma("unroll") for(int r=0;r<16;++r)pA1[r]=__builtin_amdgcn_exp2f(pA1[r]); } else { _Pragma("unroll") for(int r=0;r<16;++r)pA1[r]=__builtin_amdgcn_exp2f(fsub_s(pA1[r],mhat)); }
;   WAIT_BAR(0);
;   DMA_K(3,0);DMA_V(1,SLOTB);
;   ROT();
;   kload8(kf,kp0+sl_cur);
;   WAIT_BAR(3);
.LBB0_795:
	s_and_b64 vcc, exec, s[6:7]
	s_cbranch_vccz .LBB0_839
	v_readlane_b32 s2, v253, 6
	v_mbcnt_lo_u32_b32 v0, -1, 0
	v_mbcnt_hi_u32_b32 v0, -1, v0
	s_mov_b32 s86, 1
	s_waitcnt vmcnt(7)
	v_or_b32_e32 v46, s2, v0
	s_nop 0
	v_readfirstlane_b32 s39, v46
	s_ashr_i32 s38, s39, 6
	s_lshl_b32 s2, s38, 5
	s_ashr_i32 s3, s2, 31
	s_lshl_b64 s[2:3], s[2:3], 10
	v_and_b32_e32 v206, 63, v46
	s_add_u32 s6, s33, s2
	s_addc_u32 s7, s76, s3
	v_lshrrev_b32_e32 v2, 3, v206
	v_lshl_add_u32 v2, s38, 3, v2
	v_lshrrev_b32_e32 v3, 1, v2
	v_xor_b32_e32 v3, v3, v206
	v_and_b32_e32 v3, 7, v3
	v_lshlrev_b32_e32 v2, 10, v2
	v_lshl_add_u32 v0, v3, 4, v2
	v_lshl_add_u64 v[194:195], s[36:37], 0, v[0:1]
	s_lshl_b32 s8, s38, 4
	v_bfe_u32 v0, v46, 2, 4
	v_and_or_b32 v0, s8, 48, v0
	s_ashr_i32 s8, s39, 3
	s_andn2_b32 s8, s8, 31
	v_lshlrev_b32_e32 v0, 10, v0
	s_ashr_i32 s9, s8, 31
	s_lshl_b32 s33, s38, 10
	v_lshl_add_u64 v[2:3], s[34:35], 0, v[0:1]
	v_lshlrev_b32_e32 v209, 3, v46
	s_cmp_lg_u32 0, -1
	v_lshl_add_u64 v[2:3], s[8:9], 1, v[2:3]
	v_and_b32_e32 v211, 24, v209
	s_cselect_b32 s8, 0, 0
	v_lshlrev_b32_e32 v0, 1, v211
	s_add_i32 s33, s33, s8
	s_mov_b32 s8, m0
	s_mov_b32 m0, s33
	s_nop 0
	global_load_lds_dwordx4 v[194:195], off
	s_mov_b32 m0, s8
	v_and_b32_e32 v207, 31, v46
	v_lshl_add_u64 v[196:197], v[2:3], 0, v[0:1]
	s_add_i32 s34, s33, 0x6000
	s_mov_b32 s8, m0
	s_mov_b32 m0, s34
	s_nop 0
	global_load_lds_dwordx4 v[196:197], off
	s_mov_b32 m0, s8
	v_bfe_u32 v208, v46, 5, 1
	v_lshl_add_u64 v[198:199], v[196:197], 0, s[0:1]
	s_add_i32 s8, s33, 0x8000
	s_mov_b32 s9, m0
	s_mov_b32 m0, s8
	s_nop 0
	global_load_lds_dwordx4 v[198:199], off
	s_mov_b32 m0, s9
	s_mov_b64 s[76:77], 0x10000
	v_lshlrev_b32_e32 v0, 10, v207
	v_lshl_add_u64 v[2:3], v[194:195], 0, s[76:77]
	s_add_i32 s8, s33, 0x2000
	s_mov_b32 s9, m0
	s_mov_b32 m0, s8
	s_nop 0
	global_load_lds_dwordx4 v[2:3], off
	s_mov_b32 m0, s9
	v_lshl_or_b32 v0, v208, 4, v0
	global_load_dwordx4 v[154:157], v0, s[6:7]
	global_load_dwordx4 v[150:153], v0, s[6:7] offset:32
	global_load_dwordx4 v[142:145], v0, s[6:7] offset:64
	global_load_dwordx4 v[134:137], v0, s[6:7] offset:96
	s_mov_b64 s[6:7], 0x20000
	v_lshlrev_b32_e32 v0, 7, v207
	v_bfe_u32 v2, v207, 2, 2
	v_lshl_add_u32 v0, v2, 5, v0
	v_bfe_u32 v2, v207, 1, 1
	v_xor_b32_e32 v2, v2, v208
	v_lshl_add_u32 v212, v2, 4, v0
	v_xor_b32_e32 v217, 32, v212
	v_xor_b32_e32 v218, 64, v212
	v_xor_b32_e32 v219, 0x60, v212
	v_lshl_add_u64 v[2:3], v[194:195], 0, s[6:7]
	s_add_i32 s6, s33, 0x4000
	s_mov_b32 s7, m0
	s_mov_b32 m0, s6
	s_nop 0
	global_load_lds_dwordx4 v[2:3], off
	s_mov_b32 m0, s7
	s_waitcnt vmcnt(3) lgkmcnt(0)
	s_barrier
	ds_read_b128 v[2:5], v212
	ds_read_b128 v[6:9], v212 offset:4096
	ds_read_b128 v[34:37], v217
	ds_read_b128 v[38:41], v217 offset:4096
	s_mov_b64 s[6:7], 0x30000
	v_lshlrev_b32_e32 v0, 1, v46
	v_and_b32_e32 v213, 32, v0
	s_mov_b32 s8, 0
	s_movk_i32 s35, 0x2000
	s_movk_i32 s36, 0x4000
	s_and_b64 vcc, exec, s[4:5]
	s_waitcnt vmcnt(3) lgkmcnt(3)
	v_mfma_f32_32x32x16_bf16 v[18:33], v[2:5], v[154:157], 0
	s_waitcnt lgkmcnt(2)
	v_mfma_f32_32x32x16_bf16 v[2:17], v[6:9], v[154:157], 0
	s_waitcnt vmcnt(2) lgkmcnt(1)
	v_mfma_f32_32x32x16_bf16 v[18:33], v[34:37], v[150:153], v[18:33]
	ds_read_b128 v[34:37], v218 offset:4096
	ds_read_b128 v[42:45], v218
	s_waitcnt lgkmcnt(2)
	v_mfma_f32_32x32x16_bf16 v[2:17], v[38:41], v[150:153], v[2:17]
	s_waitcnt vmcnt(1) lgkmcnt(0)
	v_mfma_f32_32x32x16_bf16 v[18:33], v[42:45], v[142:145], v[18:33]
	ds_read_b128 v[38:41], v219 offset:4096
	ds_read_b128 v[42:45], v219
	v_mfma_f32_32x32x16_bf16 v[2:17], v[34:37], v[142:145], v[2:17]
	v_lshlrev_b32_e32 v34, 4, v46
	v_and_b32_e32 v0, 0xc0, v34
	v_lshl_or_b32 v0, v208, 8, v0
	v_add_u32_e32 v34, 0, v213
	v_add3_u32 v214, v34, v211, v0
	s_waitcnt vmcnt(0) lgkmcnt(0)
	v_mfma_f32_32x32x16_bf16 v[18:33], v[42:45], v[134:137], v[18:33]
	v_mfma_f32_32x32x16_bf16 v[2:17], v[38:41], v[134:137], v[2:17]
	s_nop 15
	s_nop 7
	s_waitcnt vmcnt(0) lgkmcnt(0)
	s_barrier
	s_nop 10
	v_exp_f32_e32 v82, v18
	v_exp_f32_e32 v83, v19
	v_exp_f32_e32 v66, v2
	v_exp_f32_e32 v67, v3
	v_lshl_add_u64 v[2:3], v[194:195], 0, s[6:7]
	s_mov_b32 s6, m0
	s_mov_b32 m0, s33
	s_nop 0
	global_load_lds_dwordx4 v[2:3], off
	s_mov_b32 m0, s6
	v_lshl_add_u64 v[2:3], v[196:197], 0, s[76:77]
	s_add_i32 s6, s33, 0xa000
	s_mov_b32 s7, m0
	s_mov_b32 m0, s6
	s_nop 0
	global_load_lds_dwordx4 v[2:3], off
	s_mov_b32 m0, s7
	s_mov_b64 s[6:7], 0x10080
	v_lshl_add_u64 v[2:3], v[196:197], 0, s[6:7]
	s_add_i32 s6, s33, 0xc000
	s_mov_b32 s7, m0
	s_mov_b32 m0, s6
	s_nop 0
	global_load_lds_dwordx4 v[2:3], off
	s_mov_b32 m0, s7
	ds_read_b128 v[186:189], v212 offset:8192
	ds_read_b128 v[174:177], v212 offset:12288
	ds_read_b128 v[190:193], v217 offset:8192
	ds_read_b128 v[178:181], v217 offset:12288
	ds_read_b128 v[182:185], v218 offset:8192
	ds_read_b128 v[166:169], v218 offset:12288
	ds_read_b128 v[170:173], v219 offset:8192
	ds_read_b128 v[162:165], v219 offset:12288
	v_exp_f32_e32 v84, v20
	v_exp_f32_e32 v85, v21
	v_exp_f32_e32 v86, v22
	v_exp_f32_e32 v87, v23
	v_exp_f32_e32 v88, v24
	v_exp_f32_e32 v89, v25
	v_exp_f32_e32 v90, v26
	v_exp_f32_e32 v91, v27
	v_exp_f32_e32 v92, v28
	v_exp_f32_e32 v93, v29
	v_exp_f32_e32 v94, v30
	v_exp_f32_e32 v95, v31
	v_exp_f32_e32 v96, v32
	v_exp_f32_e32 v97, v33
	v_exp_f32_e32 v68, v4
	v_exp_f32_e32 v69, v5
	v_exp_f32_e32 v70, v6
	v_exp_f32_e32 v71, v7
	v_exp_f32_e32 v72, v8
	v_exp_f32_e32 v73, v9
	v_exp_f32_e32 v74, v10
	v_exp_f32_e32 v75, v11
	v_exp_f32_e32 v76, v12
	v_exp_f32_e32 v77, v13
	v_exp_f32_e32 v78, v14
	v_exp_f32_e32 v79, v15
	v_exp_f32_e32 v80, v16
	v_exp_f32_e32 v81, v17
	s_waitcnt vmcnt(3) lgkmcnt(0)
	s_barrier
; template<int THRL,bool NOMAX=false> __device__ __forceinline__ void attn_unit_v128(const bf16*Qu,int qp,const bf16*__restrict__ Kh,int kp,const bf16*__restrict__ Vh,int vp,bf16*Ou,int op,int NT,char*shm,int tid_in){
;     ...
;   float mhat=0.f,l_reg=0.f;f32x16 o[4];o[0]=f32x16{};o[1]=f32x16{};o[2]=f32x16{};o[3]=f32x16{};
	s_cbranch_vccnz .LBB0_800
	v_mov_b32_e32 v210, 0
	s_mov_b32 s9, 0
	s_mov_b32 s10, 6
	s_mov_b64 s[4:5], 0
	v_mov_b32_e32 v34, 0
	v_mov_b32_e32 v35, v210
	v_mov_b32_e32 v36, v210
	v_mov_b32_e32 v37, v210
	v_mov_b32_e32 v38, v210
	v_mov_b32_e32 v39, v210
	v_mov_b32_e32 v40, v210
	v_mov_b32_e32 v41, v210
	v_mov_b32_e32 v42, v210
	v_mov_b32_e32 v43, v210
	v_mov_b32_e32 v44, v210
	v_mov_b32_e32 v45, v210
	v_mov_b32_e32 v46, v210
	v_mov_b32_e32 v47, v210
	v_mov_b32_e32 v48, v210
	v_mov_b32_e32 v49, v210
	v_mov_b32_e32 v50, 0
	v_mov_b32_e32 v51, v210
	v_mov_b32_e32 v52, v210
	v_mov_b32_e32 v53, v210
	v_mov_b32_e32 v54, v210
	v_mov_b32_e32 v55, v210
	v_mov_b32_e32 v56, v210
	v_mov_b32_e32 v57, v210
	v_mov_b32_e32 v58, v210
	v_mov_b32_e32 v59, v210
	v_mov_b32_e32 v60, v210
	v_mov_b32_e32 v61, v210
	v_mov_b32_e32 v62, v210
	v_mov_b32_e32 v63, v210
	v_mov_b32_e32 v64, v210
	v_mov_b32_e32 v65, v210
	v_mov_b32_e32 v2, 0
	v_mov_b32_e32 v3, v210
	v_mov_b32_e32 v4, v210
	v_mov_b32_e32 v5, v210
	v_mov_b32_e32 v6, v210
	v_mov_b32_e32 v7, v210
	v_mov_b32_e32 v8, v210
	v_mov_b32_e32 v9, v210
	v_mov_b32_e32 v10, v210
	v_mov_b32_e32 v11, v210
	v_mov_b32_e32 v12, v210
	v_mov_b32_e32 v13, v210
	v_mov_b32_e32 v14, v210
	v_mov_b32_e32 v15, v210
	v_mov_b32_e32 v16, v210
	v_mov_b32_e32 v17, v210
	v_mov_b32_e32 v18, 0
	v_mov_b32_e32 v19, v210
	v_mov_b32_e32 v20, v210
	v_mov_b32_e32 v21, v210
	v_mov_b32_e32 v22, v210
	v_mov_b32_e32 v23, v210
	v_mov_b32_e32 v24, v210
	v_mov_b32_e32 v25, v210
	v_mov_b32_e32 v26, v210
	v_mov_b32_e32 v27, v210
	v_mov_b32_e32 v28, v210
	v_mov_b32_e32 v29, v210
	v_mov_b32_e32 v30, v210
	v_mov_b32_e32 v31, v210
	v_mov_b32_e32 v32, v210
	v_mov_b32_e32 v33, v210
	s_mov_b64 s[12:13], 0x40000
	s_mov_b64 s[14:15], 0x20000
	s_mov_b64 s[16:17], 0x30000
	s_mov_b64 s[18:19], 0x50000
.LBB0_798:
	s_mov_b32 s8, s36
	s_mov_b32 s6, s10
	s_mov_b32 s7, s35
	v_add_f32_e32 v98, v82, v83
	v_add_f32_e32 v98, v84, v98
	v_add_f32_e32 v98, v85, v98
	v_add_f32_e32 v98, v86, v98
	v_add_f32_e32 v98, v87, v98
	v_cvt_pk_bf16_f32 v158, v82, v83
	v_cvt_pk_bf16_f32 v159, v84, v85
	v_lshl_add_u32 v201, s9, 1, v214
	s_waitcnt lgkmcnt(7)
	v_mfma_f32_32x32x16_bf16 v[114:129], v[186:189], v[154:157], 0
	s_nop 0
	v_add_f32_e32 v82, v88, v98
	v_add_f32_e32 v82, v89, v82
	v_add_f32_e32 v82, v90, v82
	v_add_f32_e32 v82, v91, v82
	v_cvt_pk_bf16_f32 v160, v86, v87
	v_cvt_pk_bf16_f32 v161, v88, v89
	s_waitcnt lgkmcnt(6)
	v_mfma_f32_32x32x16_bf16 v[98:113], v[174:177], v[154:157], 0
	v_add_f32_e32 v82, v92, v82
	v_add_f32_e32 v82, v93, v82
	v_add_f32_e32 v82, v94, v82
	v_add_f32_e32 v86, v95, v82
	v_cvt_pk_bf16_f32 v146, v90, v91
	v_cvt_pk_bf16_f32 v147, v92, v93
	s_waitcnt lgkmcnt(5)
	v_mfma_f32_32x32x16_bf16 v[114:129], v[190:193], v[150:153], v[114:129]
	ds_read_b64_tr_b16 v[82:83], v201 offset:24576
	ds_read_b64_tr_b16 v[84:85], v201 offset:25088
	v_add_f32_e32 v86, v96, v86
	v_add_f32_e32 v86, v97, v86
	v_add_f32_e32 v86, v66, v86
	v_add_f32_e32 v90, v67, v86
	v_cvt_pk_bf16_f32 v148, v94, v95
	v_cvt_pk_bf16_f32 v149, v96, v97
	s_waitcnt lgkmcnt(6)
	v_mfma_f32_32x32x16_bf16 v[98:113], v[178:181], v[150:153], v[98:113]
	ds_read_b64_tr_b16 v[86:87], v201 offset:28672
	ds_read_b64_tr_b16 v[88:89], v201 offset:29184
	v_add_f32_e32 v90, v68, v90
	v_add_f32_e32 v90, v69, v90
	v_add_f32_e32 v90, v70, v90
	v_add_f32_e32 v90, v71, v90
	v_cvt_pk_bf16_f32 v138, v66, v67
	v_cvt_pk_bf16_f32 v139, v68, v69
	s_waitcnt lgkmcnt(7)
	v_mfma_f32_32x32x16_bf16 v[114:129], v[182:185], v[142:145], v[114:129]
	ds_read_b64_tr_b16 v[66:67], v201 offset:32768
	ds_read_b64_tr_b16 v[68:69], v201 offset:33280
	v_add_f32_e32 v90, v72, v90
	v_add_f32_e32 v90, v73, v90
	v_add_f32_e32 v90, v74, v90
	v_add_f32_e32 v90, v75, v90
	v_cvt_pk_bf16_f32 v140, v70, v71
	v_cvt_pk_bf16_f32 v141, v72, v73
	s_waitcnt lgkmcnt(8)
	v_mfma_f32_32x32x16_bf16 v[98:113], v[166:169], v[142:145], v[98:113]
	ds_read_b64_tr_b16 v[70:71], v201 offset:36864
	ds_read_b64_tr_b16 v[72:73], v201 offset:37376
	v_add_f32_e32 v90, v76, v90
	v_add_f32_e32 v90, v77, v90
	v_add_f32_e32 v90, v78, v90
	v_add_f32_e32 v90, v79, v90
	v_cvt_pk_bf16_f32 v130, v74, v75
	v_cvt_pk_bf16_f32 v131, v76, v77
	s_waitcnt lgkmcnt(9)
	v_mfma_f32_32x32x16_bf16 v[114:129], v[170:173], v[134:137], v[114:129]
	ds_read_b64_tr_b16 v[74:75], v201 offset:25600
	ds_read_b64_tr_b16 v[76:77], v201 offset:26112
	v_add_f32_e32 v90, v80, v90
	v_add_f32_e32 v90, v81, v90
	v_add_f32_e32 v200, 0, v90
	v_cvt_pk_bf16_f32 v132, v78, v79
	v_cvt_pk_bf16_f32 v133, v80, v81
	s_waitcnt lgkmcnt(10)
	v_mfma_f32_32x32x16_bf16 v[98:113], v[162:165], v[134:137], v[98:113]
	v_lshl_add_u64 v[162:163], v[194:195], 0, s[4:5]
	s_add_i32 s9, s35, s33
	v_lshl_add_u64 v[78:79], v[162:163], 0, s[12:13]
	s_mov_b32 s10, m0
	s_mov_b32 m0, s9
	s_nop 0
	global_load_lds_dwordx4 v[78:79], off
	s_mov_b32 m0, s10
	v_lshl_add_u64 v[164:165], v[196:197], 0, s[4:5]
	s_lshl_b32 s9, s36, 1
	v_lshl_add_u64 v[78:79], v[164:165], 0, s[14:15]
	s_add_i32 s9, s9, s34
	s_mov_b32 s10, m0
	s_mov_b32 m0, s9
	s_nop 0
	global_load_lds_dwordx4 v[78:79], off
	s_mov_b32 m0, s10
	v_lshl_add_u64 v[166:167], v[198:199], 0, s[4:5]
	v_lshl_add_u64 v[78:79], v[166:167], 0, s[14:15]
	s_addk_i32 s9, 0x2000
	s_mov_b32 s10, m0
	s_mov_b32 m0, s9
	s_nop 0
	global_load_lds_dwordx4 v[78:79], off
	s_mov_b32 m0, s10
	s_waitcnt lgkmcnt(8)
	v_mfma_f32_32x32x16_bf16 v[34:49], v[158:161], v[82:85], v[34:49]
	v_exp_f32_e32 v114, v114
	v_exp_f32_e32 v115, v115
	ds_read_b64_tr_b16 v[78:79], v201 offset:29696
	ds_read_b64_tr_b16 v[80:81], v201 offset:30208
	s_waitcnt lgkmcnt(8)
	v_mfma_f32_32x32x16_bf16 v[50:65], v[158:161], v[86:89], v[50:65]
	v_exp_f32_e32 v116, v116
	v_exp_f32_e32 v117, v117
	ds_read_b64_tr_b16 v[82:83], v201 offset:33792
	ds_read_b64_tr_b16 v[84:85], v201 offset:34304
	s_waitcnt lgkmcnt(8)
	v_mfma_f32_32x32x16_bf16 v[2:17], v[158:161], v[66:69], v[2:17]
	v_exp_f32_e32 v118, v118
	v_exp_f32_e32 v119, v119
	ds_read_b64_tr_b16 v[86:87], v201 offset:37888
	ds_read_b64_tr_b16 v[88:89], v201 offset:38400
	s_waitcnt lgkmcnt(8)
	v_mfma_f32_32x32x16_bf16 v[18:33], v[158:161], v[70:73], v[18:33]
	v_exp_f32_e32 v120, v120
	v_exp_f32_e32 v121, v121
	ds_read_b64_tr_b16 v[70:71], v201 offset:26624
	ds_read_b64_tr_b16 v[72:73], v201 offset:27136
	v_add_u32_e32 v94, s8, v212
	v_add_u32_e32 v220, s8, v217
	v_add_u32_e32 v221, s8, v218
	v_add_u32_e32 v222, s8, v219
	ds_read_b128 v[90:93], v94
	ds_read_b128 v[66:69], v94 offset:4096
	s_waitcnt lgkmcnt(10)
	v_mfma_f32_32x32x16_bf16 v[34:49], v[146:149], v[74:77], v[34:49]
	v_exp_f32_e32 v122, v122
	v_exp_f32_e32 v123, v123
	ds_read_b64_tr_b16 v[74:75], v201 offset:30720
	ds_read_b64_tr_b16 v[76:77], v201 offset:31232
	s_waitcnt lgkmcnt(10)
	v_mfma_f32_32x32x16_bf16 v[50:65], v[146:149], v[78:81], v[50:65]
	v_exp_f32_e32 v124, v124
	v_exp_f32_e32 v125, v125
	ds_read_b64_tr_b16 v[78:79], v201 offset:34816
	ds_read_b64_tr_b16 v[80:81], v201 offset:35328
	s_waitcnt lgkmcnt(10)
	v_mfma_f32_32x32x16_bf16 v[2:17], v[146:149], v[82:85], v[2:17]
	v_exp_f32_e32 v126, v126
	v_exp_f32_e32 v127, v127
	ds_read_b64_tr_b16 v[82:83], v201 offset:38912
	ds_read_b64_tr_b16 v[84:85], v201 offset:39424
	ds_read_b128 v[168:171], v220
	ds_read_b128 v[172:175], v220 offset:4096
	s_waitcnt lgkmcnt(12)
	v_mfma_f32_32x32x16_bf16 v[18:33], v[146:149], v[86:89], v[18:33]
	v_exp_f32_e32 v128, v128
	v_exp_f32_e32 v129, v129
	ds_read_b64_tr_b16 v[86:87], v201 offset:27648
	ds_read_b64_tr_b16 v[88:89], v201 offset:28160
	s_waitcnt lgkmcnt(12)
	v_mfma_f32_32x32x16_bf16 v[34:49], v[138:141], v[70:73], v[34:49]
	v_exp_f32_e32 v98, v98
	v_exp_f32_e32 v99, v99
	ds_read_b64_tr_b16 v[70:71], v201 offset:31744
	ds_read_b64_tr_b16 v[72:73], v201 offset:32256
	s_waitcnt lgkmcnt(10)
	v_mfma_f32_32x32x16_bf16 v[50:65], v[138:141], v[74:77], v[50:65]
	v_exp_f32_e32 v100, v100
	v_exp_f32_e32 v101, v101
	ds_read_b64_tr_b16 v[74:75], v201 offset:35840
	ds_read_b64_tr_b16 v[76:77], v201 offset:36352
	ds_read_b128 v[176:179], v221
	ds_read_b128 v[180:183], v221 offset:4096
	s_waitcnt lgkmcnt(12)
	v_mfma_f32_32x32x16_bf16 v[2:17], v[138:141], v[78:81], v[2:17]
	v_exp_f32_e32 v102, v102
	v_exp_f32_e32 v103, v103
	ds_read_b64_tr_b16 v[78:79], v201 offset:39936
	ds_read_b64_tr_b16 v[80:81], v201 offset:40448
	s_waitcnt lgkmcnt(12)
	v_mfma_f32_32x32x16_bf16 v[18:33], v[138:141], v[82:85], v[18:33]
	v_exp_f32_e32 v104, v104
	v_exp_f32_e32 v105, v105
	s_waitcnt lgkmcnt(8)
	v_mfma_f32_32x32x16_bf16 v[34:49], v[130:133], v[86:89], v[34:49]
	v_exp_f32_e32 v106, v106
	v_exp_f32_e32 v107, v107
	ds_read_b128 v[184:187], v222
	ds_read_b128 v[188:191], v222 offset:4096
	s_waitcnt lgkmcnt(8)
	v_mfma_f32_32x32x16_bf16 v[50:65], v[130:133], v[70:73], v[50:65]
	v_exp_f32_e32 v108, v108
	v_exp_f32_e32 v109, v109
	s_waitcnt lgkmcnt(6)
	v_mfma_f32_32x32x16_bf16 v[2:17], v[130:133], v[74:77], v[2:17]
	v_exp_f32_e32 v110, v110
	v_exp_f32_e32 v111, v111
	s_waitcnt lgkmcnt(2)
	v_mfma_f32_32x32x16_bf16 v[18:33], v[130:133], v[78:81], v[18:33]
	v_exp_f32_e32 v112, v112
	v_exp_f32_e32 v113, v113
	s_waitcnt vmcnt(3) lgkmcnt(0)
	s_barrier
	s_add_i32 s9, s36, 0x2000
	s_cmpk_lg_i32 s36, 0x4000
	s_cselect_b32 s35, s9, 0
	v_mfma_f32_32x32x16_bf16 v[82:97], v[90:93], v[154:157], 0
	v_add_f32_e32 v70, v114, v115
	v_add_f32_e32 v70, v116, v70
	v_add_f32_e32 v70, v117, v70
	v_add_f32_e32 v70, v118, v70
	v_add_f32_e32 v70, v119, v70
	v_cvt_pk_bf16_f32 v158, v114, v115
	v_cvt_pk_bf16_f32 v159, v116, v117
	v_lshl_add_u32 v201, s7, 1, v214
	s_nop 0
	v_add_f32_e32 v70, v120, v70
	v_add_f32_e32 v70, v121, v70
	v_add_f32_e32 v70, v122, v70
	v_add_f32_e32 v114, v123, v70
	v_mfma_f32_32x32x16_bf16 v[66:81], v[66:69], v[154:157], 0
	v_cvt_pk_bf16_f32 v160, v118, v119
	v_cvt_pk_bf16_f32 v161, v120, v121
	v_mfma_f32_32x32x16_bf16 v[82:97], v[168:171], v[150:153], v[82:97]
	v_add_f32_e32 v114, v124, v114
	v_add_f32_e32 v114, v125, v114
	v_add_f32_e32 v114, v126, v114
	v_add_f32_e32 v118, v127, v114
	v_cvt_pk_bf16_f32 v146, v122, v123
	v_cvt_pk_bf16_f32 v147, v124, v125
	ds_read_b64_tr_b16 v[114:115], v201 offset:24576
	ds_read_b64_tr_b16 v[116:117], v201 offset:25088
	v_mfma_f32_32x32x16_bf16 v[66:81], v[172:175], v[150:153], v[66:81]
	v_add_f32_e32 v118, v128, v118
	v_add_f32_e32 v118, v129, v118
	v_add_f32_e32 v118, v98, v118
	v_add_f32_e32 v122, v99, v118
	v_cvt_pk_bf16_f32 v148, v126, v127
	v_cvt_pk_bf16_f32 v149, v128, v129
	ds_read_b64_tr_b16 v[118:119], v201 offset:28672
	ds_read_b64_tr_b16 v[120:121], v201 offset:29184
	v_mfma_f32_32x32x16_bf16 v[82:97], v[176:179], v[142:145], v[82:97]
	v_add_f32_e32 v122, v100, v122
	v_add_f32_e32 v122, v101, v122
	v_add_f32_e32 v122, v102, v122
	v_add_f32_e32 v122, v103, v122
	v_cvt_pk_bf16_f32 v138, v98, v99
	v_cvt_pk_bf16_f32 v139, v100, v101
	ds_read_b64_tr_b16 v[98:99], v201 offset:32768
	ds_read_b64_tr_b16 v[100:101], v201 offset:33280
	v_mfma_f32_32x32x16_bf16 v[66:81], v[180:183], v[142:145], v[66:81]
	v_add_f32_e32 v122, v104, v122
	v_add_f32_e32 v122, v105, v122
	v_add_f32_e32 v122, v106, v122
	v_add_f32_e32 v122, v107, v122
	v_cvt_pk_bf16_f32 v140, v102, v103
	v_cvt_pk_bf16_f32 v141, v104, v105
	ds_read_b64_tr_b16 v[102:103], v201 offset:36864
	ds_read_b64_tr_b16 v[104:105], v201 offset:37376
	s_waitcnt lgkmcnt(9)
; #define WAIT_BAR(N) asm volatile("s_waitcnt vmcnt(" #N ") lgkmcnt(0)\n\ts_barrier":::"memory")
;   #define RESC() do{ if(resc){ asm volatile("s_waitcnt lgkmcnt(0)":::"memory"); \
;       _Pragma("unroll") for(int d_=0;d_<2;++d_) _Pragma("unroll") for(int r=0;r<16;++r)o[d_][r]*=wsf[crow(r,hi)]; } }while(0)
;   #define ROT() do{sl_prev=sl_cur;sl_cur=sl_next;sl_next=(sl_next==(NSLOT-1)*SLOTB)?0:sl_next+SLOTB;}while(0)
;   #define RESC() do{ if(resc){ asm volatile("s_waitcnt lgkmcnt(0)":::"memory"); \
;       _Pragma("unroll") for(int d_=0;d_<4;++d_) _Pragma("unroll") for(int r=0;r<16;++r)o[d_][r]*=wsf[crow(r,hi)]; } }while(0)
;   #define ROT() do{sl_prev=sl_cur;sl_cur=sl_next;sl_next=(sl_next==(NSLOT-1)*SLOTB)?0:sl_next+SLOTB;}while(0)
; template<int THRL,bool NOMAX=false> __device__ __forceinline__ void attn_unit_v128(const bf16*Qu,int qp,const bf16*__restrict__ Kh,int kp,const bf16*__restrict__ Vh,int vp,bf16*Ou,int op,int NT,char*shm,int tid_in){
;     ...
;   int t=1;
;   for(;t+5<NT;t+=2){
;     STEP(pB0,pB1,pA0,pA1,t,true,true,true);     WAIT_BAR(3); RESC(); ROT();
;     STEP(pA0,pA1,pB0,pB1,t+1,true,true,true);   WAIT_BAR(3); RESC(); ROT();
	v_mfma_f32_32x32x16_bf16 v[82:97], v[184:187], v[134:137], v[82:97]
	v_add_f32_e32 v122, v108, v122
	v_add_f32_e32 v122, v109, v122
	v_add_f32_e32 v122, v110, v122
	v_add_f32_e32 v122, v111, v122
	v_cvt_pk_bf16_f32 v130, v106, v107
	v_cvt_pk_bf16_f32 v131, v108, v109
	ds_read_b64_tr_b16 v[106:107], v201 offset:25600
	ds_read_b64_tr_b16 v[108:109], v201 offset:26112
	s_waitcnt lgkmcnt(10)
	v_mfma_f32_32x32x16_bf16 v[66:81], v[188:191], v[134:137], v[66:81]
	v_add_f32_e32 v122, v112, v122
	v_add_f32_e32 v122, v113, v122
	v_add_f32_e32 v122, 0, v122
	v_cvt_pk_bf16_f32 v132, v110, v111
	v_cvt_pk_bf16_f32 v133, v112, v113
	s_add_i32 s7, s36, s33
	v_lshl_add_u64 v[110:111], v[162:163], 0, s[18:19]
	s_mov_b32 s9, m0
	s_mov_b32 m0, s7
	s_nop 0
	global_load_lds_dwordx4 v[110:111], off
	s_mov_b32 m0, s9
	s_lshl_b32 s7, s35, 1
	v_lshl_add_u64 v[110:111], v[164:165], 0, s[16:17]
	s_add_i32 s7, s7, s34
	s_mov_b32 s9, m0
	s_mov_b32 m0, s7
	s_nop 0
	global_load_lds_dwordx4 v[110:111], off
	s_mov_b32 m0, s9
	v_lshl_add_u64 v[110:111], v[166:167], 0, s[16:17]
	s_addk_i32 s7, 0x2000
	s_mov_b32 s9, m0
	s_mov_b32 m0, s7
	s_nop 0
	global_load_lds_dwordx4 v[110:111], off
	s_mov_b32 m0, s9
	s_waitcnt lgkmcnt(8)
	v_mfma_f32_32x32x16_bf16 v[34:49], v[158:161], v[114:117], v[34:49]
	v_exp_f32_e32 v82, v82
	v_exp_f32_e32 v83, v83
	ds_read_b64_tr_b16 v[110:111], v201 offset:29696
	ds_read_b64_tr_b16 v[112:113], v201 offset:30208
	s_waitcnt lgkmcnt(8)
	v_mfma_f32_32x32x16_bf16 v[50:65], v[158:161], v[118:121], v[50:65]
	v_exp_f32_e32 v84, v84
	v_exp_f32_e32 v85, v85
	ds_read_b64_tr_b16 v[114:115], v201 offset:33792
	ds_read_b64_tr_b16 v[116:117], v201 offset:34304
	s_waitcnt lgkmcnt(8)
	v_mfma_f32_32x32x16_bf16 v[2:17], v[158:161], v[98:101], v[2:17]
	v_exp_f32_e32 v86, v86
	v_exp_f32_e32 v87, v87
	ds_read_b64_tr_b16 v[98:99], v201 offset:37888
	ds_read_b64_tr_b16 v[100:101], v201 offset:38400
	s_waitcnt lgkmcnt(8)
	v_mfma_f32_32x32x16_bf16 v[18:33], v[158:161], v[102:105], v[18:33]
	v_exp_f32_e32 v88, v88
	v_exp_f32_e32 v89, v89
	ds_read_b64_tr_b16 v[102:103], v201 offset:26624
	ds_read_b64_tr_b16 v[104:105], v201 offset:27136
	v_add_u32_e32 v118, s35, v212
	v_add_u32_e32 v220, s35, v217
	v_add_u32_e32 v221, s35, v218
	v_add_u32_e32 v222, s35, v219
	ds_read_b128 v[186:189], v118
	ds_read_b128 v[174:177], v118 offset:4096
	s_waitcnt lgkmcnt(10)
	v_mfma_f32_32x32x16_bf16 v[34:49], v[146:149], v[106:109], v[34:49]
	v_exp_f32_e32 v90, v90
	v_exp_f32_e32 v91, v91
	ds_read_b64_tr_b16 v[106:107], v201 offset:30720
	ds_read_b64_tr_b16 v[108:109], v201 offset:31232
	s_waitcnt lgkmcnt(10)
	v_mfma_f32_32x32x16_bf16 v[50:65], v[146:149], v[110:113], v[50:65]
	v_exp_f32_e32 v92, v92
	v_exp_f32_e32 v93, v93
	ds_read_b64_tr_b16 v[110:111], v201 offset:34816
	ds_read_b64_tr_b16 v[112:113], v201 offset:35328
	s_waitcnt lgkmcnt(10)
	v_mfma_f32_32x32x16_bf16 v[2:17], v[146:149], v[114:117], v[2:17]
	v_exp_f32_e32 v94, v94
	v_exp_f32_e32 v95, v95
	ds_read_b64_tr_b16 v[114:115], v201 offset:38912
	ds_read_b64_tr_b16 v[116:117], v201 offset:39424
	ds_read_b128 v[190:193], v220
	ds_read_b128 v[178:181], v220 offset:4096
	s_waitcnt lgkmcnt(12)
	v_mfma_f32_32x32x16_bf16 v[18:33], v[146:149], v[98:101], v[18:33]
	v_exp_f32_e32 v96, v96
	v_exp_f32_e32 v97, v97
	ds_read_b64_tr_b16 v[98:99], v201 offset:27648
	ds_read_b64_tr_b16 v[100:101], v201 offset:28160
	s_waitcnt lgkmcnt(12)
	v_mfma_f32_32x32x16_bf16 v[34:49], v[138:141], v[102:105], v[34:49]
	v_exp_f32_e32 v66, v66
	v_exp_f32_e32 v67, v67
	ds_read_b64_tr_b16 v[102:103], v201 offset:31744
	ds_read_b64_tr_b16 v[104:105], v201 offset:32256
	s_waitcnt lgkmcnt(10)
	v_mfma_f32_32x32x16_bf16 v[50:65], v[138:141], v[106:109], v[50:65]
	v_exp_f32_e32 v68, v68
	v_exp_f32_e32 v69, v69
	ds_read_b64_tr_b16 v[106:107], v201 offset:35840
	ds_read_b64_tr_b16 v[108:109], v201 offset:36352
	ds_read_b128 v[182:185], v221
	ds_read_b128 v[166:169], v221 offset:4096
	s_waitcnt lgkmcnt(12)
	v_mfma_f32_32x32x16_bf16 v[2:17], v[138:141], v[110:113], v[2:17]
	v_exp_f32_e32 v70, v70
	v_exp_f32_e32 v71, v71
	ds_read_b64_tr_b16 v[110:111], v201 offset:39936
	ds_read_b64_tr_b16 v[112:113], v201 offset:40448
	s_waitcnt lgkmcnt(12)
	v_mfma_f32_32x32x16_bf16 v[18:33], v[138:141], v[114:117], v[18:33]
	v_exp_f32_e32 v72, v72
	v_exp_f32_e32 v73, v73
	s_waitcnt lgkmcnt(8)
	v_mfma_f32_32x32x16_bf16 v[34:49], v[130:133], v[98:101], v[34:49]
	v_exp_f32_e32 v74, v74
	v_exp_f32_e32 v75, v75
	ds_read_b128 v[170:173], v222
	ds_read_b128 v[162:165], v222 offset:4096
	s_waitcnt lgkmcnt(8)
	v_mfma_f32_32x32x16_bf16 v[50:65], v[130:133], v[102:105], v[50:65]
	v_exp_f32_e32 v76, v76
	v_exp_f32_e32 v77, v77
	s_waitcnt lgkmcnt(6)
	v_mfma_f32_32x32x16_bf16 v[2:17], v[130:133], v[106:109], v[2:17]
	v_exp_f32_e32 v78, v78
	v_exp_f32_e32 v79, v79
	s_waitcnt lgkmcnt(2)
	v_mfma_f32_32x32x16_bf16 v[18:33], v[130:133], v[110:113], v[18:33]
	v_exp_f32_e32 v80, v80
	v_exp_f32_e32 v81, v81
	s_add_i32 s7, s35, 0x2000
	s_cmpk_lg_i32 s35, 0x4000
	s_mov_b32 s9, s36
	s_cselect_b32 s36, s7, 0
	s_add_i32 s10, s6, 2
	s_waitcnt vmcnt(3) lgkmcnt(0)
	s_barrier
	s_add_u32 s4, s4, 0x20000
	v_add_f32_e32 v98, v210, v200
	s_addc_u32 s5, s5, 0
	s_cmp_ge_u32 s10, s75
	v_add_f32_e32 v210, v98, v122
	s_cbranch_scc0 .LBB0_798
	s_add_i32 s86, s6, -3
	s_add_i32 s4, s86, 1
	s_cmp_ge_u32 s4, s75
	s_mov_b64 s[4:5], -1
	s_cbranch_scc0 .LBB0_802
	s_branch .LBB0_801

;   #define RESC() do{ if(resc){ asm volatile("s_waitcnt lgkmcnt(0)":::"memory"); \
;       _Pragma("unroll") for(int d_=0;d_<2;++d_) _Pragma("unroll") for(int r=0;r<16;++r)o[d_][r]*=wsf[crow(r,hi)]; } }while(0)
;   #define ROT() do{sl_prev=sl_cur;sl_cur=sl_next;sl_next=(sl_next==(NSLOT-1)*SLOTB)?0:sl_next+SLOTB;}while(0)
;   #define ENDW(tt) do{ if((tt)+3<NT){WAIT_BAR(2);} else if((tt)+2<NT){WAIT_BAR(1);} else {WAIT_BAR(0);} }while(0)
;   #define RESC() do{ if(resc){ asm volatile("s_waitcnt lgkmcnt(0)":::"memory"); \
;       _Pragma("unroll") for(int d_=0;d_<4;++d_) _Pragma("unroll") for(int r=0;r<16;++r)o[d_][r]*=wsf[crow(r,hi)]; } }while(0)
;   #define ROT() do{sl_prev=sl_cur;sl_cur=sl_next;sl_next=(sl_next==(NSLOT-1)*SLOTB)?0:sl_next+SLOTB;}while(0)
;   #define ENDW(tt) do{ if((tt)+3<NT){WAIT_BAR(3);} else if((tt)+2<NT){WAIT_BAR(2);} else {WAIT_BAR(0);} }while(0)
; template<int THRL,bool NOMAX=false> __device__ __forceinline__ void attn_unit_v128(const bf16*Qu,int qp,const bf16*__restrict__ Kh,int kp,const bf16*__restrict__ Vh,int vp,bf16*Ou,int op,int NT,char*shm,int tid_in){
;     ...
;   for(;t+1<NT;t+=2){
;     STEP(pB0,pB1,pA0,pA1,t,(t+3<NT),(t+1<NT),(t+1<NT));       ENDW(t);   RESC(); ROT();
;     STEP(pA0,pA1,pB0,pB1,t+1,(t+4<NT),(t+2<NT),(t+2<NT));     ENDW(t+1); RESC(); ROT();
;   }
.LBB0_806:
	v_lshl_add_u64 v[200:201], v[196:197], 0, s[6:7]
	s_mov_b64 s[10:11], 0x10000
	s_lshl_b32 s15, s36, 1
	v_lshl_add_u64 v[78:79], v[200:201], 0, s[10:11]
	s_add_i32 s4, s15, s34
	s_mov_b32 s5, m0
	s_mov_b32 m0, s4
	s_nop 0
	global_load_lds_dwordx4 v[78:79], off
	s_mov_b32 m0, s5
	v_lshl_add_u64 v[204:205], v[198:199], 0, s[6:7]
	v_lshl_add_u64 v[78:79], v[204:205], 0, s[10:11]
	s_addk_i32 s4, 0x2000
	s_mov_b32 s5, m0
	s_mov_b32 m0, s4
	s_nop 0
	global_load_lds_dwordx4 v[78:79], off
	s_mov_b32 m0, s5
	s_waitcnt lgkmcnt(8)
	v_mfma_f32_32x32x16_bf16 v[34:49], v[158:161], v[82:85], v[34:49]
	v_exp_f32_e32 v114, v114
	v_exp_f32_e32 v115, v115
	ds_read_b64_tr_b16 v[78:79], v216 offset:29696
	ds_read_b64_tr_b16 v[80:81], v216 offset:30208
	s_waitcnt lgkmcnt(8)
	v_mfma_f32_32x32x16_bf16 v[50:65], v[158:161], v[86:89], v[50:65]
	v_exp_f32_e32 v116, v116
	v_exp_f32_e32 v117, v117
	ds_read_b64_tr_b16 v[82:83], v216 offset:33792
	ds_read_b64_tr_b16 v[84:85], v216 offset:34304
	s_waitcnt lgkmcnt(8)
	v_mfma_f32_32x32x16_bf16 v[2:17], v[158:161], v[66:69], v[2:17]
	v_exp_f32_e32 v118, v118
	v_exp_f32_e32 v119, v119
	ds_read_b64_tr_b16 v[66:67], v216 offset:37888
	ds_read_b64_tr_b16 v[68:69], v216 offset:38400
	s_waitcnt lgkmcnt(8)
	v_mfma_f32_32x32x16_bf16 v[18:33], v[158:161], v[70:73], v[18:33]
	v_exp_f32_e32 v120, v120
	v_exp_f32_e32 v121, v121
	ds_read_b64_tr_b16 v[70:71], v216 offset:26624
	ds_read_b64_tr_b16 v[72:73], v216 offset:27136
	v_add_u32_e32 v86, s36, v212
	v_add_u32_e32 v220, s36, v217
	v_add_u32_e32 v221, s36, v218
	v_add_u32_e32 v222, s36, v219
	ds_read_b128 v[186:189], v86
	ds_read_b128 v[174:177], v86 offset:4096
	s_waitcnt lgkmcnt(10)
	v_mfma_f32_32x32x16_bf16 v[34:49], v[146:149], v[74:77], v[34:49]
	v_exp_f32_e32 v122, v122
	v_exp_f32_e32 v123, v123
	ds_read_b64_tr_b16 v[74:75], v216 offset:30720
	ds_read_b64_tr_b16 v[76:77], v216 offset:31232
	s_waitcnt lgkmcnt(10)
	v_mfma_f32_32x32x16_bf16 v[50:65], v[146:149], v[78:81], v[50:65]
	v_exp_f32_e32 v124, v124
	v_exp_f32_e32 v125, v125
	ds_read_b64_tr_b16 v[78:79], v216 offset:34816
	ds_read_b64_tr_b16 v[80:81], v216 offset:35328
	s_waitcnt lgkmcnt(10)
	v_mfma_f32_32x32x16_bf16 v[2:17], v[146:149], v[82:85], v[2:17]
	v_exp_f32_e32 v126, v126
	v_exp_f32_e32 v127, v127
	ds_read_b64_tr_b16 v[82:83], v216 offset:38912
	ds_read_b64_tr_b16 v[84:85], v216 offset:39424
	ds_read_b128 v[190:193], v220
	ds_read_b128 v[178:181], v220 offset:4096
	s_waitcnt lgkmcnt(12)
	v_mfma_f32_32x32x16_bf16 v[18:33], v[146:149], v[66:69], v[18:33]
	v_exp_f32_e32 v128, v128
	v_exp_f32_e32 v129, v129
	ds_read_b64_tr_b16 v[66:67], v216 offset:27648
	ds_read_b64_tr_b16 v[68:69], v216 offset:28160
	s_waitcnt lgkmcnt(12)
	v_mfma_f32_32x32x16_bf16 v[34:49], v[138:141], v[70:73], v[34:49]
	v_exp_f32_e32 v98, v98
	v_exp_f32_e32 v99, v99
	ds_read_b64_tr_b16 v[70:71], v216 offset:31744
	ds_read_b64_tr_b16 v[72:73], v216 offset:32256
	s_waitcnt lgkmcnt(10)
	v_mfma_f32_32x32x16_bf16 v[50:65], v[138:141], v[74:77], v[50:65]
	v_exp_f32_e32 v100, v100
	v_exp_f32_e32 v101, v101
	ds_read_b64_tr_b16 v[74:75], v216 offset:35840
	ds_read_b64_tr_b16 v[76:77], v216 offset:36352
	ds_read_b128 v[182:185], v221
	ds_read_b128 v[166:169], v221 offset:4096
	s_waitcnt lgkmcnt(12)
	v_mfma_f32_32x32x16_bf16 v[2:17], v[138:141], v[78:81], v[2:17]
	v_exp_f32_e32 v102, v102
	v_exp_f32_e32 v103, v103
	ds_read_b64_tr_b16 v[78:79], v216 offset:39936
	ds_read_b64_tr_b16 v[80:81], v216 offset:40448
	s_waitcnt lgkmcnt(12)
	v_mfma_f32_32x32x16_bf16 v[18:33], v[138:141], v[82:85], v[18:33]
	v_exp_f32_e32 v104, v104
	v_exp_f32_e32 v105, v105
	s_waitcnt lgkmcnt(8)
	v_mfma_f32_32x32x16_bf16 v[34:49], v[130:133], v[66:69], v[34:49]
	v_exp_f32_e32 v106, v106
	v_exp_f32_e32 v107, v107
	ds_read_b128 v[170:173], v222
	ds_read_b128 v[162:165], v222 offset:4096
	s_waitcnt lgkmcnt(8)
	v_mfma_f32_32x32x16_bf16 v[50:65], v[130:133], v[70:73], v[50:65]
	v_exp_f32_e32 v108, v108
	v_exp_f32_e32 v109, v109
	s_waitcnt lgkmcnt(6)
	v_mfma_f32_32x32x16_bf16 v[2:17], v[130:133], v[74:77], v[2:17]
	v_exp_f32_e32 v110, v110
	v_exp_f32_e32 v111, v111
	s_waitcnt lgkmcnt(2)
	v_mfma_f32_32x32x16_bf16 v[18:33], v[130:133], v[78:81], v[18:33]
	v_exp_f32_e32 v112, v112
	v_exp_f32_e32 v113, v113
	s_mov_b64 s[4:5], -1
	s_and_b64 vcc, exec, s[8:9]
	s_cbranch_vccz .LBB0_812
	s_add_i32 s4, s16, -2
	s_cmp_ge_u32 s4, s14
	s_mov_b64 s[4:5], -1
	s_cbranch_scc0 .LBB0_809
	s_waitcnt vmcnt(0) lgkmcnt(0)
	s_barrier
	s_mov_b64 s[4:5], 0

;   #define RESC() do{ if(resc){ asm volatile("s_waitcnt lgkmcnt(0)":::"memory"); \
;       _Pragma("unroll") for(int d_=0;d_<2;++d_) _Pragma("unroll") for(int r=0;r<16;++r)o[d_][r]*=wsf[crow(r,hi)]; } }while(0)
;   #define ROT() do{sl_prev=sl_cur;sl_cur=sl_next;sl_next=(sl_next==(NSLOT-1)*SLOTB)?0:sl_next+SLOTB;}while(0)
;   #define ENDW(tt) do{ if((tt)+3<NT){WAIT_BAR(2);} else if((tt)+2<NT){WAIT_BAR(1);} else {WAIT_BAR(0);} }while(0)
;   #define RESC() do{ if(resc){ asm volatile("s_waitcnt lgkmcnt(0)":::"memory"); \
;       _Pragma("unroll") for(int d_=0;d_<4;++d_) _Pragma("unroll") for(int r=0;r<16;++r)o[d_][r]*=wsf[crow(r,hi)]; } }while(0)
;   #define ROT() do{sl_prev=sl_cur;sl_cur=sl_next;sl_next=(sl_next==(NSLOT-1)*SLOTB)?0:sl_next+SLOTB;}while(0)
;   #define ENDW(tt) do{ if((tt)+3<NT){WAIT_BAR(3);} else if((tt)+2<NT){WAIT_BAR(2);} else {WAIT_BAR(0);} }while(0)
; template<int THRL,bool NOMAX=false> __device__ __forceinline__ void attn_unit_v128(const bf16*Qu,int qp,const bf16*__restrict__ Kh,int kp,const bf16*__restrict__ Vh,int vp,bf16*Ou,int op,int NT,char*shm,int tid_in){
;     ...
;   for(;t+1<NT;t+=2){
;     STEP(pB0,pB1,pA0,pA1,t,(t+3<NT),(t+1<NT),(t+1<NT));       ENDW(t);   RESC(); ROT();
;     STEP(pA0,pA1,pB0,pB1,t+1,(t+4<NT),(t+2<NT),(t+2<NT));     ENDW(t+1); RESC(); ROT();
;   }
.LBB0_818:
	s_waitcnt lgkmcnt(8)
	v_mfma_f32_32x32x16_bf16 v[34:49], v[158:161], v[114:117], v[34:49]
	v_exp_f32_e32 v82, v82
	v_exp_f32_e32 v83, v83
	ds_read_b64_tr_b16 v[110:111], v216 offset:29696
	ds_read_b64_tr_b16 v[112:113], v216 offset:30208
	s_waitcnt lgkmcnt(8)
	v_mfma_f32_32x32x16_bf16 v[50:65], v[158:161], v[118:121], v[50:65]
	v_exp_f32_e32 v84, v84
	v_exp_f32_e32 v85, v85
	ds_read_b64_tr_b16 v[114:115], v216 offset:33792
	ds_read_b64_tr_b16 v[116:117], v216 offset:34304
	s_waitcnt lgkmcnt(8)
	v_mfma_f32_32x32x16_bf16 v[2:17], v[158:161], v[122:125], v[2:17]
	v_exp_f32_e32 v86, v86
	v_exp_f32_e32 v87, v87
	ds_read_b64_tr_b16 v[106:107], v216 offset:37888
	ds_read_b64_tr_b16 v[108:109], v216 offset:38400
	s_waitcnt lgkmcnt(8)
	v_mfma_f32_32x32x16_bf16 v[18:33], v[158:161], v[102:105], v[18:33]
	v_exp_f32_e32 v88, v88
	v_exp_f32_e32 v89, v89
	ds_read_b64_tr_b16 v[102:103], v216 offset:26624
	ds_read_b64_tr_b16 v[104:105], v216 offset:27136
	v_cndmask_b32_e64 v118, 0, 1, s[12:13]
	v_cmp_ne_u32_e64 s[4:5], 1, v118
	s_andn2_b64 vcc, exec, s[12:13]
	v_add_u32_e32 v122, s35, v212
	v_add_u32_e32 v220, s35, v217
	v_add_u32_e32 v221, s35, v218
	v_add_u32_e32 v222, s35, v219
	s_cbranch_vccnz .LBB0_820
	ds_read_b128 v[186:189], v122
	ds_read_b128 v[174:177], v122 offset:4096
.LBB0_820:
	s_waitcnt lgkmcnt(8)
	v_mfma_f32_32x32x16_bf16 v[34:49], v[146:149], v[98:101], v[34:49]
	v_exp_f32_e32 v90, v90
	v_exp_f32_e32 v91, v91
	ds_read_b64_tr_b16 v[118:119], v216 offset:30720
	ds_read_b64_tr_b16 v[120:121], v216 offset:31232
	s_waitcnt lgkmcnt(8)
	v_mfma_f32_32x32x16_bf16 v[50:65], v[146:149], v[110:113], v[50:65]
	v_exp_f32_e32 v92, v92
	v_exp_f32_e32 v93, v93
	ds_read_b64_tr_b16 v[110:111], v216 offset:34816
	ds_read_b64_tr_b16 v[112:113], v216 offset:35328
	s_waitcnt lgkmcnt(8)
	v_mfma_f32_32x32x16_bf16 v[2:17], v[146:149], v[114:117], v[2:17]
	v_exp_f32_e32 v94, v94
	v_exp_f32_e32 v95, v95
	ds_read_b64_tr_b16 v[98:99], v216 offset:38912
	ds_read_b64_tr_b16 v[100:101], v216 offset:39424
	s_and_b64 vcc, exec, s[4:5]
	s_cbranch_vccnz .LBB0_822
	ds_read_b128 v[190:193], v220
	ds_read_b128 v[178:181], v220 offset:4096
.LBB0_822:
	s_waitcnt lgkmcnt(8)
	v_mfma_f32_32x32x16_bf16 v[18:33], v[146:149], v[106:109], v[18:33]
	v_exp_f32_e32 v96, v96
	v_exp_f32_e32 v97, v97
	ds_read_b64_tr_b16 v[114:115], v216 offset:27648
	ds_read_b64_tr_b16 v[116:117], v216 offset:28160
	s_waitcnt lgkmcnt(8)
	v_mfma_f32_32x32x16_bf16 v[34:49], v[138:141], v[102:105], v[34:49]
	v_exp_f32_e32 v66, v66
	v_exp_f32_e32 v67, v67
	ds_read_b64_tr_b16 v[102:103], v216 offset:31744
	ds_read_b64_tr_b16 v[104:105], v216 offset:32256
	s_waitcnt lgkmcnt(8)
	v_mfma_f32_32x32x16_bf16 v[50:65], v[138:141], v[118:121], v[50:65]
	v_exp_f32_e32 v68, v68
	v_exp_f32_e32 v69, v69
	ds_read_b64_tr_b16 v[106:107], v216 offset:35840
	ds_read_b64_tr_b16 v[108:109], v216 offset:36352
	s_and_b64 vcc, exec, s[4:5]
	s_cbranch_vccnz .LBB0_824
	ds_read_b128 v[182:185], v221
	ds_read_b128 v[166:169], v221 offset:4096
.LBB0_824:
	s_waitcnt lgkmcnt(8)
	v_mfma_f32_32x32x16_bf16 v[2:17], v[138:141], v[110:113], v[2:17]
	v_exp_f32_e32 v70, v70
	v_exp_f32_e32 v71, v71
	ds_read_b64_tr_b16 v[110:111], v216 offset:39936
	ds_read_b64_tr_b16 v[112:113], v216 offset:40448
	s_waitcnt lgkmcnt(8)
	v_mfma_f32_32x32x16_bf16 v[18:33], v[138:141], v[98:101], v[18:33]
	v_exp_f32_e32 v72, v72
	v_exp_f32_e32 v73, v73
	s_waitcnt lgkmcnt(6)
	v_mfma_f32_32x32x16_bf16 v[34:49], v[130:133], v[114:117], v[34:49]
	v_exp_f32_e32 v74, v74
	v_exp_f32_e32 v75, v75
	s_and_b64 vcc, exec, s[4:5]
	s_cbranch_vccnz .LBB0_826
	ds_read_b128 v[170:173], v222
	ds_read_b128 v[162:165], v222 offset:4096
